# residual+LN epilogue: second half of the X stores issued after the row-statistics arrival signal (wave 0 after the statistics read), on top of the combined build
# speedup vs baseline: 1.0012x; 1.0012x over previous
;   __device__ __forceinline__ void operator()(f32x4 (&acc)[2][2][4][2], int pm, int pn, int wr_, int wc_, int fr_, int fq_, bf16_t* shm, int tid) const {
;     ...
;         for (int ai = 0; ai < 2; ++ai)
; #pragma unroll
;           for (int m = 0; m < 4; ++m) {
;             const int row = pm * 256 + ai * 128 + wr * 64 + m * 16 + fr;
;             const f32x4 v = acc[ai][bj][m][n];
;             f32x4* xp = (f32x4*)(X + (long)row * DM + col);
;             f32x4 xv = *(const f32x4*)(Xr + (long)row * DM + col);
;             if (stats) { const float mu = stats[2 * row], rs = stats[2 * row + 1]; xv = (xv - mu) * rs * lg + lb; }
;             xv = xv * ALPHA + gv * v; *xp = xv;
;             acc[ai][bj][m][n] = xv;
.Lres_r1_skip16:
	v_pk_mul_f32 v[166:167], v[166:167], s[92:93] op_sel_hi:[1,0]
	v_pk_mul_f32 v[168:169], v[168:169], s[92:93] op_sel_hi:[1,0]
	v_pk_fma_f32 v[62:63], v[62:63], v[236:237], v[166:167]
	v_pk_fma_f32 v[64:65], v[64:65], v[238:239], v[168:169]
	global_load_dwordx4 v[166:169], v221, s[52:53] offset:576
	s_waitcnt vmcnt(27)
	s_cbranch_vccnz .Lres_r1_skip17
	v_sub_f32_e32 v173, v173, v132
	v_sub_f32_e32 v172, v172, v132
	v_sub_f32_e32 v171, v171, v132
	v_sub_f32_e32 v170, v170, v132
	v_pk_mul_f32 v[170:171], v[170:171], v[132:133] op_sel:[0,1]
	v_pk_mul_f32 v[172:173], v[172:173], v[132:133] op_sel:[0,1]
	v_pk_fma_f32 v[170:171], v[228:229], v[170:171], v[232:233]
	v_pk_fma_f32 v[172:173], v[230:231], v[172:173], v[234:235]
.Lres_r1_skip17:
	v_pk_mul_f32 v[170:171], v[170:171], s[92:93] op_sel_hi:[1,0]
	v_pk_mul_f32 v[172:173], v[172:173], s[92:93] op_sel_hi:[1,0]
	v_pk_fma_f32 v[70:71], v[70:71], v[236:237], v[170:171]
	v_pk_fma_f32 v[72:73], v[72:73], v[238:239], v[172:173]
	global_load_dwordx4 v[170:173], v222, s[52:53] offset:576
	s_waitcnt vmcnt(26)
	s_cbranch_vccnz .Lres_r1_skip18
	v_sub_f32_e32 v177, v177, v134
	v_sub_f32_e32 v176, v176, v134
	v_sub_f32_e32 v175, v175, v134
	v_sub_f32_e32 v174, v174, v134
	v_pk_mul_f32 v[174:175], v[174:175], v[134:135] op_sel:[0,1]
	v_pk_mul_f32 v[176:177], v[176:177], v[134:135] op_sel:[0,1]
	v_pk_fma_f32 v[174:175], v[228:229], v[174:175], v[232:233]
	v_pk_fma_f32 v[176:177], v[230:231], v[176:177], v[234:235]
.Lres_r1_skip18:
	v_pk_mul_f32 v[174:175], v[174:175], s[92:93] op_sel_hi:[1,0]
	v_pk_mul_f32 v[176:177], v[176:177], s[92:93] op_sel_hi:[1,0]
	v_pk_fma_f32 v[74:75], v[74:75], v[236:237], v[174:175]
	v_pk_fma_f32 v[76:77], v[76:77], v[238:239], v[176:177]
	global_load_dwordx4 v[174:177], v223, s[52:53] offset:576
	s_waitcnt vmcnt(25)
	s_cbranch_vccnz .Lres_r1_skip19
	v_sub_f32_e32 v181, v181, v136
	v_sub_f32_e32 v180, v180, v136
	v_sub_f32_e32 v179, v179, v136
	v_sub_f32_e32 v178, v178, v136
	v_pk_mul_f32 v[178:179], v[178:179], v[136:137] op_sel:[0,1]
	v_pk_mul_f32 v[180:181], v[180:181], v[136:137] op_sel:[0,1]
	v_pk_fma_f32 v[178:179], v[228:229], v[178:179], v[232:233]
	v_pk_fma_f32 v[180:181], v[230:231], v[180:181], v[234:235]
.Lres_r1_skip19:
	v_pk_mul_f32 v[178:179], v[178:179], s[92:93] op_sel_hi:[1,0]
	v_pk_mul_f32 v[180:181], v[180:181], s[92:93] op_sel_hi:[1,0]
	v_pk_fma_f32 v[78:79], v[78:79], v[236:237], v[178:179]
	v_pk_fma_f32 v[80:81], v[80:81], v[238:239], v[180:181]
	global_load_dwordx4 v[178:181], v224, s[52:53] offset:576
	s_waitcnt vmcnt(21)
	s_cbranch_vccnz .Lres_r1_skip20
	v_sub_f32_e32 v185, v185, v138
	v_sub_f32_e32 v184, v184, v138
	v_sub_f32_e32 v183, v183, v138
	v_sub_f32_e32 v182, v182, v138
	v_pk_mul_f32 v[182:183], v[182:183], v[138:139] op_sel:[0,1]
	v_pk_mul_f32 v[184:185], v[184:185], v[138:139] op_sel:[0,1]
	v_pk_fma_f32 v[182:183], v[228:229], v[182:183], v[232:233]
	v_pk_fma_f32 v[184:185], v[230:231], v[184:185], v[234:235]
.Lres_r1_skip20:
	v_pk_mul_f32 v[182:183], v[182:183], s[92:93] op_sel_hi:[1,0]
	v_pk_mul_f32 v[184:185], v[184:185], s[92:93] op_sel_hi:[1,0]
	v_pk_fma_f32 v[82:83], v[82:83], v[236:237], v[182:183]
	v_pk_fma_f32 v[84:85], v[84:85], v[238:239], v[184:185]
	s_waitcnt vmcnt(19)
	s_cbranch_vccnz .Lres_r1_skip21
	v_sub_f32_e32 v189, v189, v140
	v_sub_f32_e32 v188, v188, v140
	v_sub_f32_e32 v187, v187, v140
	v_sub_f32_e32 v186, v186, v140
	v_pk_mul_f32 v[186:187], v[186:187], v[140:141] op_sel:[0,1]
	v_pk_mul_f32 v[188:189], v[188:189], v[140:141] op_sel:[0,1]
	v_pk_fma_f32 v[186:187], v[228:229], v[186:187], v[232:233]
	v_pk_fma_f32 v[188:189], v[230:231], v[188:189], v[234:235]
.Lres_r1_skip21:
	v_pk_mul_f32 v[186:187], v[186:187], s[92:93] op_sel_hi:[1,0]
	v_pk_mul_f32 v[188:189], v[188:189], s[92:93] op_sel_hi:[1,0]
	v_pk_fma_f32 v[86:87], v[86:87], v[236:237], v[186:187]
	v_pk_fma_f32 v[88:89], v[88:89], v[238:239], v[188:189]
	s_waitcnt vmcnt(17)
	s_cbranch_vccnz .Lres_r1_skip22
	v_sub_f32_e32 v193, v193, v142
	v_sub_f32_e32 v192, v192, v142
	v_sub_f32_e32 v191, v191, v142
	v_sub_f32_e32 v190, v190, v142
	v_pk_mul_f32 v[190:191], v[190:191], v[142:143] op_sel:[0,1]
	v_pk_mul_f32 v[192:193], v[192:193], v[142:143] op_sel:[0,1]
	v_pk_fma_f32 v[190:191], v[228:229], v[190:191], v[232:233]
	v_pk_fma_f32 v[192:193], v[230:231], v[192:193], v[234:235]
.Lres_r1_skip22:
	v_pk_mul_f32 v[190:191], v[190:191], s[92:93] op_sel_hi:[1,0]
	v_pk_mul_f32 v[192:193], v[192:193], s[92:93] op_sel_hi:[1,0]
	v_pk_fma_f32 v[90:91], v[90:91], v[236:237], v[190:191]
	v_pk_fma_f32 v[92:93], v[92:93], v[238:239], v[192:193]
	s_waitcnt vmcnt(15)
	s_cbranch_vccnz .Lres_r1_skip23
	v_sub_f32_e32 v197, v197, v144
	v_sub_f32_e32 v196, v196, v144
	v_sub_f32_e32 v195, v195, v144
	v_sub_f32_e32 v194, v194, v144
	v_pk_mul_f32 v[194:195], v[194:195], v[144:145] op_sel:[0,1]
	v_pk_mul_f32 v[196:197], v[196:197], v[144:145] op_sel:[0,1]
	v_pk_fma_f32 v[194:195], v[228:229], v[194:195], v[232:233]
	v_pk_fma_f32 v[196:197], v[230:231], v[196:197], v[234:235]
.Lres_r1_skip23:
	v_pk_mul_f32 v[194:195], v[194:195], s[92:93] op_sel_hi:[1,0]
	v_pk_mul_f32 v[196:197], v[196:197], s[92:93] op_sel_hi:[1,0]
	v_pk_fma_f32 v[102:103], v[102:103], v[236:237], v[194:195]
	v_pk_fma_f32 v[104:105], v[104:105], v[238:239], v[196:197]
	s_waitcnt vmcnt(4)
	s_cbranch_vccnz .Lres_r1_skip24
	v_sub_f32_e32 v153, v153, v130
	v_sub_f32_e32 v152, v152, v130
	v_sub_f32_e32 v151, v151, v130
	v_sub_f32_e32 v150, v150, v130
	v_pk_mul_f32 v[150:151], v[150:151], v[130:131] op_sel:[0,1]
	v_pk_mul_f32 v[152:153], v[152:153], v[130:131] op_sel:[0,1]
	v_pk_fma_f32 v[150:151], v[240:241], v[150:151], v[244:245]
	v_pk_fma_f32 v[152:153], v[242:243], v[152:153], v[246:247]
;   __device__ __forceinline__ void operator()(f32x4 (&acc)[2][2][4][2], int pm, int pn, int wr_, int wc_, int fr_, int fq_, bf16_t* shm, int tid) const {
;     ...
;         for (int ai = 0; ai < 2; ++ai)
; #pragma unroll
;           for (int m = 0; m < 4; ++m) {
;             const int row = pm * 256 + ai * 128 + wr * 64 + m * 16 + fr;
;             const f32x4 v = acc[ai][bj][m][n];
;             f32x4* xp = (f32x4*)(X + (long)row * DM + col);
;             f32x4 xv = *(const f32x4*)(Xr + (long)row * DM + col);
;             if (stats) { const float mu = stats[2 * row], rs = stats[2 * row + 1]; xv = (xv - mu) * rs * lg + lb; }
;             xv = xv * ALPHA + gv * v; *xp = xv;
;             acc[ai][bj][m][n] = xv;
.Lres_r1_skip24:
	v_pk_mul_f32 v[150:151], v[150:151], s[92:93] op_sel_hi:[1,0]
	v_pk_mul_f32 v[152:153], v[152:153], s[92:93] op_sel_hi:[1,0]
	v_pk_fma_f32 v[98:99], v[98:99], v[198:199], v[150:151]
	v_pk_fma_f32 v[100:101], v[100:101], v[200:201], v[152:153]
	s_waitcnt vmcnt(11)
	s_cbranch_vccnz .Lres_r1_skip25
	v_sub_f32_e32 v157, v157, v132
	v_sub_f32_e32 v156, v156, v132
	v_sub_f32_e32 v155, v155, v132
	v_sub_f32_e32 v154, v154, v132
	v_pk_mul_f32 v[154:155], v[154:155], v[132:133] op_sel:[0,1]
	v_pk_mul_f32 v[156:157], v[156:157], v[132:133] op_sel:[0,1]
	v_pk_fma_f32 v[154:155], v[240:241], v[154:155], v[244:245]
	v_pk_fma_f32 v[156:157], v[242:243], v[156:157], v[246:247]
.Lres_r1_skip25:
	v_pk_mul_f32 v[154:155], v[154:155], s[92:93] op_sel_hi:[1,0]
	v_pk_mul_f32 v[156:157], v[156:157], s[92:93] op_sel_hi:[1,0]
	v_pk_fma_f32 v[106:107], v[106:107], v[198:199], v[154:155]
	v_pk_fma_f32 v[108:109], v[108:109], v[200:201], v[156:157]
	s_waitcnt vmcnt(9)
	s_cbranch_vccnz .Lres_r1_skip26
	v_sub_f32_e32 v161, v161, v134
	v_sub_f32_e32 v160, v160, v134
	v_sub_f32_e32 v159, v159, v134
	v_sub_f32_e32 v158, v158, v134
	v_pk_mul_f32 v[158:159], v[158:159], v[134:135] op_sel:[0,1]
	v_pk_mul_f32 v[160:161], v[160:161], v[134:135] op_sel:[0,1]
	v_pk_fma_f32 v[158:159], v[240:241], v[158:159], v[244:245]
	v_pk_fma_f32 v[160:161], v[242:243], v[160:161], v[246:247]
.Lres_r1_skip26:
	v_pk_mul_f32 v[158:159], v[158:159], s[92:93] op_sel_hi:[1,0]
	v_pk_mul_f32 v[160:161], v[160:161], s[92:93] op_sel_hi:[1,0]
	v_pk_fma_f32 v[110:111], v[110:111], v[198:199], v[158:159]
	v_pk_fma_f32 v[112:113], v[112:113], v[200:201], v[160:161]
	s_waitcnt vmcnt(7)
	s_cbranch_vccnz .Lres_r1_skip27
	v_sub_f32_e32 v165, v165, v136
	v_sub_f32_e32 v164, v164, v136
	v_sub_f32_e32 v163, v163, v136
	v_sub_f32_e32 v162, v162, v136
	v_pk_mul_f32 v[162:163], v[162:163], v[136:137] op_sel:[0,1]
	v_pk_mul_f32 v[164:165], v[164:165], v[136:137] op_sel:[0,1]
	v_pk_fma_f32 v[162:163], v[240:241], v[162:163], v[244:245]
	v_pk_fma_f32 v[164:165], v[242:243], v[164:165], v[246:247]
.Lres_r1_skip27:
	v_pk_mul_f32 v[162:163], v[162:163], s[92:93] op_sel_hi:[1,0]
	v_pk_mul_f32 v[164:165], v[164:165], s[92:93] op_sel_hi:[1,0]
	v_pk_fma_f32 v[114:115], v[114:115], v[198:199], v[162:163]
	v_pk_fma_f32 v[116:117], v[116:117], v[200:201], v[164:165]
	s_waitcnt vmcnt(3)
	s_cbranch_vccnz .Lres_r1_skip28
	v_sub_f32_e32 v169, v169, v138
	v_sub_f32_e32 v168, v168, v138
	v_sub_f32_e32 v167, v167, v138
	v_sub_f32_e32 v166, v166, v138
	v_pk_mul_f32 v[166:167], v[166:167], v[138:139] op_sel:[0,1]
	v_pk_mul_f32 v[168:169], v[168:169], v[138:139] op_sel:[0,1]
	v_pk_fma_f32 v[166:167], v[240:241], v[166:167], v[244:245]
	v_pk_fma_f32 v[168:169], v[242:243], v[168:169], v[246:247]
.Lres_r1_skip28:
	v_pk_mul_f32 v[166:167], v[166:167], s[92:93] op_sel_hi:[1,0]
	v_pk_mul_f32 v[168:169], v[168:169], s[92:93] op_sel_hi:[1,0]
	v_pk_fma_f32 v[122:123], v[122:123], v[198:199], v[166:167]
	v_pk_fma_f32 v[124:125], v[124:125], v[200:201], v[168:169]
	s_waitcnt vmcnt(2)
	s_cbranch_vccnz .Lres_r1_skip29
	v_sub_f32_e32 v173, v173, v140
	v_sub_f32_e32 v172, v172, v140
	v_sub_f32_e32 v171, v171, v140
	v_sub_f32_e32 v170, v170, v140
	v_pk_mul_f32 v[170:171], v[170:171], v[140:141] op_sel:[0,1]
	v_pk_mul_f32 v[172:173], v[172:173], v[140:141] op_sel:[0,1]
	v_pk_fma_f32 v[170:171], v[240:241], v[170:171], v[244:245]
	v_pk_fma_f32 v[172:173], v[242:243], v[172:173], v[246:247]
.Lres_r1_skip29:
	v_pk_mul_f32 v[170:171], v[170:171], s[92:93] op_sel_hi:[1,0]
	v_pk_mul_f32 v[172:173], v[172:173], s[92:93] op_sel_hi:[1,0]
	v_pk_fma_f32 v[126:127], v[126:127], v[198:199], v[170:171]
	v_pk_fma_f32 v[128:129], v[128:129], v[200:201], v[172:173]
	s_waitcnt vmcnt(1)
	s_cbranch_vccnz .Lres_r1_skip30
	v_sub_f32_e32 v177, v177, v142
	v_sub_f32_e32 v176, v176, v142
	v_sub_f32_e32 v175, v175, v142
	v_sub_f32_e32 v174, v174, v142
	v_pk_mul_f32 v[174:175], v[174:175], v[142:143] op_sel:[0,1]
	v_pk_mul_f32 v[176:177], v[176:177], v[142:143] op_sel:[0,1]
	v_pk_fma_f32 v[174:175], v[240:241], v[174:175], v[244:245]
	v_pk_fma_f32 v[176:177], v[242:243], v[176:177], v[246:247]
;   __device__ __forceinline__ void operator()(f32x4 (&acc)[2][2][4][2], int pm, int pn, int wr_, int wc_, int fr_, int fq_, bf16_t* shm, int tid) const {
;     ...
;         for (int ai = 0; ai < 2; ++ai)
; #pragma unroll
;           for (int m = 0; m < 4; ++m) {
;             const int row = pm * 256 + ai * 128 + wr * 64 + m * 16 + fr;
;             const f32x4 v = acc[ai][bj][m][n];
;             f32x4* xp = (f32x4*)(X + (long)row * DM + col);
;             f32x4 xv = *(const f32x4*)(Xr + (long)row * DM + col);
;             if (stats) { const float mu = stats[2 * row], rs = stats[2 * row + 1]; xv = (xv - mu) * rs * lg + lb; }
;             xv = xv * ALPHA + gv * v; *xp = xv;
;             acc[ai][bj][m][n] = xv;
;             s1[ai * 4 + m] += (xv[0] + xv[1]) + (xv[2] + xv[3]);
;             s2[ai * 4 + m] += (xv[0] * xv[0] + xv[1] * xv[1]) + (xv[2] * xv[2] + xv[3] * xv[3]);
;           }
;       }
; #pragma unroll
;     for (int i = 0; i < 8; ++i) {
;       s1[i] += __shfl_xor(s1[i], 16); s1[i] += __shfl_xor(s1[i], 32);
;       s2[i] += __shfl_xor(s2[i], 16); s2[i] += __shfl_xor(s2[i], 32);
;       if (fq == 0) red[((i >> 2) * 128 + wr * 64 + (i & 3) * 16 + fr) * 4 + wc] = (f2_t){s1[i], s2[i]};
.Lres_r1_skip30:
	v_pk_mul_f32 v[174:175], v[174:175], s[92:93] op_sel_hi:[1,0]
	v_pk_mul_f32 v[176:177], v[176:177], s[92:93] op_sel_hi:[1,0]
	v_pk_fma_f32 v[118:119], v[118:119], v[198:199], v[174:175]
	v_pk_fma_f32 v[120:121], v[120:121], v[200:201], v[176:177]
	s_waitcnt vmcnt(0)
	s_cbranch_vccnz .Lres_r1_skip31
	v_sub_f32_e32 v181, v181, v144
	v_sub_f32_e32 v180, v180, v144
	v_sub_f32_e32 v179, v179, v144
	v_sub_f32_e32 v178, v178, v144
	v_pk_mul_f32 v[178:179], v[178:179], v[144:145] op_sel:[0,1]
	v_pk_mul_f32 v[180:181], v[180:181], v[144:145] op_sel:[0,1]
	v_pk_fma_f32 v[178:179], v[240:241], v[178:179], v[244:245]
	v_pk_fma_f32 v[180:181], v[242:243], v[180:181], v[246:247]
.Lres_r1_skip31:
	v_pk_mul_f32 v[178:179], v[178:179], s[92:93] op_sel_hi:[1,0]
	v_pk_mul_f32 v[180:181], v[180:181], s[92:93] op_sel_hi:[1,0]
	v_pk_fma_f32 v[94:95], v[94:95], v[198:199], v[178:179]
	v_pk_fma_f32 v[96:97], v[96:97], v[200:201], v[180:181]
.LBB0_200:
	v_mov_b32_e32 v134, v4
	v_mov_b32_e32 v135, v2
	v_mov_b32_e32 v136, v5
	v_mov_b32_e32 v137, v2
	v_pk_add_f32 v[138:139], v[134:135], v[136:137]
	v_pk_mul_f32 v[134:135], v[134:135], v[136:137]
	v_pk_mul_f32 v[136:137], v[2:3], v[2:3]
	v_mov_b32_e32 v139, v135
	v_pk_add_f32 v[134:135], v[2:3], v[2:3] op_sel:[1,0]
	v_mul_f32_e32 v136, v4, v4
	v_mov_b32_e32 v135, v137
	v_pk_fma_f32 v[136:137], v[4:5], v[4:5], v[136:137] op_sel_hi:[1,1,0]
	v_pk_add_f32 v[134:135], v[134:135], v[138:139]
	v_mov_b32_e32 v136, v1
	v_pk_add_f32 v[134:135], v[134:135], v[136:137]
	v_mul_f32_e32 v137, v30, v30
	v_mul_f32_e32 v139, v31, v31
	v_mul_f32_e32 v141, v32, v32
	v_mul_f32_e32 v153, v33, v33
	v_mov_b32_e32 v136, v30
	v_mov_b32_e32 v138, v31
	v_mov_b32_e32 v140, v32
	v_mov_b32_e32 v152, v33
	v_pk_add_f32 v[136:137], v[136:137], v[138:139]
	v_pk_add_f32 v[138:139], v[140:141], v[152:153]
	v_mul_f32_e32 v141, v64, v64
	v_pk_add_f32 v[136:137], v[136:137], v[138:139]
	v_mul_f32_e32 v139, v63, v63
	v_pk_add_f32 v[134:135], v[134:135], v[136:137]
	v_mul_f32_e32 v137, v62, v62
	v_mul_f32_e32 v153, v65, v65
	v_mov_b32_e32 v136, v62
	v_mov_b32_e32 v138, v63
	v_mov_b32_e32 v140, v64
	v_mov_b32_e32 v152, v65
	v_pk_add_f32 v[136:137], v[136:137], v[138:139]
	v_pk_add_f32 v[138:139], v[140:141], v[152:153]
	v_mul_f32_e32 v141, v100, v100
	v_pk_add_f32 v[136:137], v[136:137], v[138:139]
	v_mul_f32_e32 v139, v99, v99
	v_pk_add_f32 v[134:135], v[134:135], v[136:137]
	v_mul_f32_e32 v137, v98, v98
	v_mul_f32_e32 v153, v101, v101
	v_mov_b32_e32 v136, v98
	v_mov_b32_e32 v138, v99
	v_mov_b32_e32 v140, v100
	v_mov_b32_e32 v152, v101
	v_pk_add_f32 v[136:137], v[136:137], v[138:139]
	v_pk_add_f32 v[138:139], v[140:141], v[152:153]
	v_readlane_b32 s6, v253, 26
	v_pk_add_f32 v[136:137], v[136:137], v[138:139]
	v_pk_add_f32 v[136:137], v[134:135], v[136:137]
	v_and_b32_e32 v131, 64, v226
	v_xor_b32_e32 v130, 16, v226
	v_add_u32_e32 v132, 64, v131
	v_cmp_lt_i32_e32 vcc, v130, v132
	v_xor_b32_e32 v133, 32, v226
	v_or_b32_e32 v154, v214, v149
	v_cndmask_b32_e32 v130, v226, v130, vcc
	v_lshlrev_b32_e32 v134, 2, v130
	v_mov_b32_e32 v130, v136
	v_mov_b32_e32 v131, v137
	s_nop 1
	v_permlane16_swap_b32_e32 v130, v136
	v_permlane16_swap_b32_e32 v131, v137
	v_cmp_lt_i32_e32 vcc, v133, v132
	s_waitcnt lgkmcnt(0)
	v_pk_add_f32 v[130:131], v[136:137], v[130:131]
	v_cndmask_b32_e32 v132, v226, v133, vcc
	v_lshlrev_b32_e32 v135, 2, v132
	v_mov_b32_e32 v132, v130
	v_mov_b32_e32 v133, v131
	s_nop 1
	v_permlane32_swap_b32_e32 v132, v130
	v_permlane32_swap_b32_e32 v133, v131
	v_lshl_add_u32 v136, v215, 3, s6
	v_cmp_eq_u32_e32 vcc, 0, v216
	v_lshl_add_u32 v137, v154, 5, v136
	s_and_saveexec_b64 s[6:7], vcc
	s_cbranch_execz .LBB0_202
	s_waitcnt lgkmcnt(0)
	v_pk_add_f32 v[130:131], v[130:131], v[132:133]
	ds_write_b64 v137, v[130:131]

;   __device__ __forceinline__ void operator()(f32x4 (&acc)[2][2][4][2], int pm, int pn, int wr_, int wc_, int fr_, int fq_, bf16_t* shm, int tid) const {
;     ...
;     asm volatile("s_waitcnt vmcnt(0)" ::: "memory");
;     __syncthreads();
;     if (tid == 0) {
;       __hip_atomic_fetch_add(cnt + pm * 16, 1u, __ATOMIC_RELAXED, __HIP_MEMORY_SCOPE_AGENT);
;       unsigned sp = 0;
;       while (__hip_atomic_load(cnt + pm * 16, __ATOMIC_RELAXED, __HIP_MEMORY_SCOPE_AGENT) < 4u * gen) { __builtin_amdgcn_s_sleep(1); if (++sp > (1u << 22)) break; }
;     }
.LBB0_218:
	s_or_b64 exec, exec, s[6:7]
	s_waitcnt vmcnt(0)
	v_cmp_eq_u32_e32 vcc, 0, v148
	s_barrier
	v_readlane_b32 s98, v250, 0
	s_cmp_eq_u32 s98, 0
	s_cbranch_scc1 .Lres_r1_dq
	global_store_dwordx4 v217, v[62:65], s[54:55] offset:512
	global_store_dwordx4 v218, v[70:73], s[54:55] offset:512
	global_store_dwordx4 v219, v[74:77], s[54:55] offset:512
	global_store_dwordx4 v220, v[78:81], s[54:55] offset:512
	global_store_dwordx4 v221, v[82:85], s[54:55] offset:512
	global_store_dwordx4 v222, v[86:89], s[54:55] offset:512
	global_store_dwordx4 v223, v[90:93], s[54:55] offset:512
	global_store_dwordx4 v224, v[102:105], s[54:55] offset:512
	global_store_dwordx4 v217, v[98:101], s[54:55] offset:576
	global_store_dwordx4 v218, v[106:109], s[54:55] offset:576
	global_store_dwordx4 v219, v[110:113], s[54:55] offset:576
	global_store_dwordx4 v220, v[114:117], s[54:55] offset:576
	global_store_dwordx4 v221, v[122:125], s[54:55] offset:576
	global_store_dwordx4 v222, v[126:129], s[54:55] offset:576
	global_store_dwordx4 v223, v[118:121], s[54:55] offset:576
	global_store_dwordx4 v224, v[94:97], s[54:55] offset:576
.Lres_r1_dq:
	s_and_saveexec_b64 s[6:7], vcc
	s_cbranch_execz .LBB0_229
	s_lshl_b32 s14, s10, 4
	s_mov_b64 s[40:41], exec
	s_ashr_i32 s15, s14, 31
	s_lshl_b64 s[14:15], s[14:15], 2
	v_readlane_b32 s18, v253, 36
	v_mbcnt_lo_u32_b32 v130, s40, 0
	v_readlane_b32 s19, v253, 37
	s_add_u32 s14, s18, s14
	v_mbcnt_hi_u32_b32 v130, s41, v130
	s_addc_u32 s15, s19, s15
	v_cmp_eq_u32_e32 vcc, 0, v130
	s_and_saveexec_b64 s[42:43], vcc
	s_cbranch_execz .LBB0_221
	s_bcnt1_i32_b64 s11, s[40:41]
	v_mov_b32_e32 v130, s11
	global_atomic_add v1, v130, s[14:15]

;   __device__ __forceinline__ void operator()(f32x4 (&acc)[2][2][4][2], int pm, int pn, int wr_, int wc_, int fr_, int fq_, bf16_t* shm, int tid) const {
;     ...
;     if (tid < 256) {
;       float S1 = 0.f, S2 = 0.f;
; #pragma unroll
;       for (int q = 0; q < 4; ++q) { const f2_t t = __builtin_bit_cast(f2_t, __hip_atomic_load(xch + ((long)pm * 4 + q) * 256 + tid, __ATOMIC_RELAXED, __HIP_MEMORY_SCOPE_AGENT)); S1 += t[0]; S2 += t[1]; }
;       const float mu = S1 * (1.f / 1024.f), var = fmaxf(S2 * (1.f / 1024.f) - mu * mu, 0.f), rs = rsqrtf(var + EPS);
;       rst[tid] = (f2_t){mu, rs};
;       if (pn == 0 && !outp) { lnst[2 * (pm * 256 + tid)] = mu; lnst[2 * (pm * 256 + tid) + 1] = rs; }
;     }
;     __syncthreads();
; #pragma unroll
;     for (int bj = 0; bj < 2; ++bj)
; #pragma unroll
;       for (int n = 0; n < 2; ++n) {
;         asm volatile("" ::: "memory");
;         const int col = pn * 256 + bj * 128 + wc * 32 + n * 16 + fq * 4;
;         const f32x4 gg = *(const f32x4*)(ng + col), bb = *(const f32x4*)(nb + col);
;         f32x4 sh = {0.f, 0.f, 0.f, 0.f}, sc = {0.f, 0.f, 0.f, 0.f};
;         if (!outp) { sh = *(const f32x4*)(msh + bio + col); sc = *(const f32x4*)(msc + bio + col); }
.LBB0_232:
	s_or_b64 exec, exec, s[6:7]
	v_readlane_b32 s98, v250, 0
	s_cmp_lg_u32 s98, 0
	s_cbranch_scc1 .Lres_r1_dq0
	v_readlane_b32 s98, v252, 24
	v_readlane_b32 s99, v252, 25
	s_nop 4
	global_store_dwordx4 v217, v[62:65], s[98:99] offset:512
	global_store_dwordx4 v218, v[70:73], s[98:99] offset:512
	global_store_dwordx4 v219, v[74:77], s[98:99] offset:512
	global_store_dwordx4 v220, v[78:81], s[98:99] offset:512
	global_store_dwordx4 v221, v[82:85], s[98:99] offset:512
	global_store_dwordx4 v222, v[86:89], s[98:99] offset:512
	global_store_dwordx4 v223, v[90:93], s[98:99] offset:512
	global_store_dwordx4 v224, v[102:105], s[98:99] offset:512
	global_store_dwordx4 v217, v[98:101], s[98:99] offset:576
	global_store_dwordx4 v218, v[106:109], s[98:99] offset:576
	global_store_dwordx4 v219, v[110:113], s[98:99] offset:576
	global_store_dwordx4 v220, v[114:117], s[98:99] offset:576
	global_store_dwordx4 v221, v[122:125], s[98:99] offset:576
	global_store_dwordx4 v222, v[126:129], s[98:99] offset:576
	global_store_dwordx4 v223, v[118:121], s[98:99] offset:576
	global_store_dwordx4 v224, v[94:97], s[98:99] offset:576
.Lres_r1_dq0:
	s_waitcnt lgkmcnt(0)
	s_barrier
	v_lshl_add_u64 v[158:159], s[88:89], 0, v[146:147]
	v_lshl_add_u64 v[160:161], s[66:67], 0, v[146:147]
	global_load_dwordx4 v[134:137], v[158:159], off
	global_load_dwordx4 v[138:141], v[160:161], off
	global_load_dwordx4 v[176:179], v[158:159], off offset:64
	global_load_dwordx4 v[180:183], v[160:161], off offset:64
	global_load_dwordx4 v[192:195], v[158:159], off offset:512
	global_load_dwordx4 v[196:199], v[160:161], off offset:512
	global_load_dwordx4 v[222:225], v[158:159], off offset:576
	global_load_dwordx4 v[228:231], v[160:161], off offset:576
	s_add_u32 s6, s77, s0
	s_addc_u32 s7, s90, s1
	s_add_u32 s0, s76, s0
	v_cndmask_b32_e64 v130, 0, 1, s[12:13]
	s_addc_u32 s1, s23, s1
	v_cmp_ne_u32_e64 s[10:11], 1, v130
	s_andn2_b64 vcc, exec, s[12:13]
	s_cbranch_vccz .LBB0_237
	v_mov_b32_e32 v162, 1.0
	v_mov_b32_e32 v130, 0
	v_mov_b32_e32 v131, v130
	v_mov_b32_e32 v132, v130
	v_mov_b32_e32 v133, v130
	v_mov_b32_e32 v163, v162
	v_mov_b32_e32 v164, v162
	v_mov_b32_e32 v165, v162
	s_branch .LBB0_238

;   __device__ __forceinline__ void operator()(f32x4 (&acc)[2][2][4][2], int pm, int pn, int wr_, int wc_, int fr_, int fq_, bf16_t* shm, int tid) const {
;     ...
;         for (int ai = 0; ai < 2; ++ai)
; #pragma unroll
;           for (int m = 0; m < 4; ++m) {
;             const int row = pm * 256 + ai * 128 + wr * 64 + m * 16 + fr;
;             const f32x4 v = acc[ai][bj][m][n];
;             f32x4* xp = (f32x4*)(X + (long)row * DM + col);
;             f32x4 xv = *(const f32x4*)(Xr + (long)row * DM + col);
;             if (stats) { const float mu = stats[2 * row], rs = stats[2 * row + 1]; xv = (xv - mu) * rs * lg + lb; }
;             xv = xv * ALPHA + gv * v; *xp = xv;
;             acc[ai][bj][m][n] = xv;
.Lres_r2_skip16:
	v_pk_mul_f32 v[166:167], v[166:167], s[92:93] op_sel_hi:[1,0]
	v_pk_mul_f32 v[168:169], v[168:169], s[92:93] op_sel_hi:[1,0]
	v_pk_fma_f32 v[98:99], v[98:99], v[206:207], v[166:167]
	v_pk_fma_f32 v[100:101], v[100:101], v[208:209], v[168:169]
	global_load_dwordx4 v[166:169], v227, s[52:53] offset:576
	s_waitcnt vmcnt(27)
	s_cbranch_vccnz .Lres_r2_skip17
	v_sub_f32_e32 v173, v173, v132
	v_sub_f32_e32 v172, v172, v132
	v_sub_f32_e32 v171, v171, v132
	v_sub_f32_e32 v170, v170, v132
	v_pk_mul_f32 v[170:171], v[170:171], v[132:133] op_sel:[0,1]
	v_pk_mul_f32 v[172:173], v[172:173], v[132:133] op_sel:[0,1]
	v_pk_fma_f32 v[170:171], v[198:199], v[170:171], v[202:203]
	v_pk_fma_f32 v[172:173], v[200:201], v[172:173], v[204:205]
.Lres_r2_skip17:
	v_pk_mul_f32 v[170:171], v[170:171], s[92:93] op_sel_hi:[1,0]
	v_pk_mul_f32 v[172:173], v[172:173], s[92:93] op_sel_hi:[1,0]
	v_pk_fma_f32 v[102:103], v[102:103], v[206:207], v[170:171]
	v_pk_fma_f32 v[104:105], v[104:105], v[208:209], v[172:173]
	global_load_dwordx4 v[170:173], v232, s[52:53] offset:576
	s_waitcnt vmcnt(26)
	s_cbranch_vccnz .Lres_r2_skip18
	v_sub_f32_e32 v177, v177, v134
	v_sub_f32_e32 v176, v176, v134
	v_sub_f32_e32 v175, v175, v134
	v_sub_f32_e32 v174, v174, v134
	v_pk_mul_f32 v[174:175], v[174:175], v[134:135] op_sel:[0,1]
	v_pk_mul_f32 v[176:177], v[176:177], v[134:135] op_sel:[0,1]
	v_pk_fma_f32 v[174:175], v[198:199], v[174:175], v[202:203]
	v_pk_fma_f32 v[176:177], v[200:201], v[176:177], v[204:205]
.Lres_r2_skip18:
	v_pk_mul_f32 v[174:175], v[174:175], s[92:93] op_sel_hi:[1,0]
	v_pk_mul_f32 v[176:177], v[176:177], s[92:93] op_sel_hi:[1,0]
	v_pk_fma_f32 v[90:91], v[90:91], v[206:207], v[174:175]
	v_pk_fma_f32 v[92:93], v[92:93], v[208:209], v[176:177]
	global_load_dwordx4 v[174:177], v233, s[52:53] offset:576
	s_waitcnt vmcnt(25)
	s_cbranch_vccnz .Lres_r2_skip19
	v_sub_f32_e32 v181, v181, v136
	v_sub_f32_e32 v180, v180, v136
	v_sub_f32_e32 v179, v179, v136
	v_sub_f32_e32 v178, v178, v136
	v_pk_mul_f32 v[178:179], v[178:179], v[136:137] op_sel:[0,1]
	v_pk_mul_f32 v[180:181], v[180:181], v[136:137] op_sel:[0,1]
	v_pk_fma_f32 v[178:179], v[198:199], v[178:179], v[202:203]
	v_pk_fma_f32 v[180:181], v[200:201], v[180:181], v[204:205]
.Lres_r2_skip19:
	v_pk_mul_f32 v[178:179], v[178:179], s[92:93] op_sel_hi:[1,0]
	v_pk_mul_f32 v[180:181], v[180:181], s[92:93] op_sel_hi:[1,0]
	v_pk_fma_f32 v[22:23], v[22:23], v[206:207], v[178:179]
	v_pk_fma_f32 v[24:25], v[24:25], v[208:209], v[180:181]
	global_load_dwordx4 v[178:181], v245, s[52:53] offset:576
	s_waitcnt vmcnt(21)
	s_cbranch_vccnz .Lres_r2_skip20
	v_sub_f32_e32 v185, v185, v138
	v_sub_f32_e32 v184, v184, v138
	v_sub_f32_e32 v183, v183, v138
	v_sub_f32_e32 v182, v182, v138
	v_pk_mul_f32 v[182:183], v[182:183], v[138:139] op_sel:[0,1]
	v_pk_mul_f32 v[184:185], v[184:185], v[138:139] op_sel:[0,1]
	v_pk_fma_f32 v[182:183], v[198:199], v[182:183], v[202:203]
	v_pk_fma_f32 v[184:185], v[200:201], v[184:185], v[204:205]
.Lres_r2_skip20:
	v_pk_mul_f32 v[182:183], v[182:183], s[92:93] op_sel_hi:[1,0]
	v_pk_mul_f32 v[184:185], v[184:185], s[92:93] op_sel_hi:[1,0]
	v_pk_fma_f32 v[34:35], v[34:35], v[206:207], v[182:183]
	v_pk_fma_f32 v[36:37], v[36:37], v[208:209], v[184:185]
	s_waitcnt vmcnt(19)
	s_cbranch_vccnz .Lres_r2_skip21
	v_sub_f32_e32 v189, v189, v140
	v_sub_f32_e32 v188, v188, v140
	v_sub_f32_e32 v187, v187, v140
	v_sub_f32_e32 v186, v186, v140
	v_pk_mul_f32 v[186:187], v[186:187], v[140:141] op_sel:[0,1]
	v_pk_mul_f32 v[188:189], v[188:189], v[140:141] op_sel:[0,1]
	v_pk_fma_f32 v[186:187], v[198:199], v[186:187], v[202:203]
	v_pk_fma_f32 v[188:189], v[200:201], v[188:189], v[204:205]
.Lres_r2_skip21:
	v_pk_mul_f32 v[186:187], v[186:187], s[92:93] op_sel_hi:[1,0]
	v_pk_mul_f32 v[188:189], v[188:189], s[92:93] op_sel_hi:[1,0]
	v_pk_fma_f32 v[42:43], v[42:43], v[206:207], v[186:187]
	v_pk_fma_f32 v[44:45], v[44:45], v[208:209], v[188:189]
	s_waitcnt vmcnt(17)
	s_cbranch_vccnz .Lres_r2_skip22
	v_sub_f32_e32 v193, v193, v142
	v_sub_f32_e32 v192, v192, v142
	v_sub_f32_e32 v191, v191, v142
	v_sub_f32_e32 v190, v190, v142
	v_pk_mul_f32 v[190:191], v[190:191], v[142:143] op_sel:[0,1]
	v_pk_mul_f32 v[192:193], v[192:193], v[142:143] op_sel:[0,1]
	v_pk_fma_f32 v[190:191], v[198:199], v[190:191], v[202:203]
	v_pk_fma_f32 v[192:193], v[200:201], v[192:193], v[204:205]
.Lres_r2_skip22:
	v_pk_mul_f32 v[190:191], v[190:191], s[92:93] op_sel_hi:[1,0]
	v_pk_mul_f32 v[192:193], v[192:193], s[92:93] op_sel_hi:[1,0]
	v_pk_fma_f32 v[62:63], v[62:63], v[206:207], v[190:191]
	v_pk_fma_f32 v[64:65], v[64:65], v[208:209], v[192:193]
	s_waitcnt vmcnt(15)
	s_cbranch_vccnz .Lres_r2_skip23
	v_sub_f32_e32 v197, v197, v144
	v_sub_f32_e32 v196, v196, v144
	v_sub_f32_e32 v195, v195, v144
	v_sub_f32_e32 v194, v194, v144
	v_pk_mul_f32 v[194:195], v[194:195], v[144:145] op_sel:[0,1]
	v_pk_mul_f32 v[196:197], v[196:197], v[144:145] op_sel:[0,1]
	v_pk_fma_f32 v[194:195], v[198:199], v[194:195], v[202:203]
	v_pk_fma_f32 v[196:197], v[200:201], v[196:197], v[204:205]
.Lres_r2_skip23:
	v_pk_mul_f32 v[194:195], v[194:195], s[92:93] op_sel_hi:[1,0]
	v_pk_mul_f32 v[196:197], v[196:197], s[92:93] op_sel_hi:[1,0]
	v_pk_fma_f32 v[74:75], v[74:75], v[206:207], v[194:195]
	v_pk_fma_f32 v[76:77], v[76:77], v[208:209], v[196:197]
	s_waitcnt vmcnt(4)
	s_cbranch_vccnz .Lres_r2_skip24
	v_sub_f32_e32 v153, v153, v130
	v_sub_f32_e32 v152, v152, v130
	v_sub_f32_e32 v151, v151, v130
	v_sub_f32_e32 v150, v150, v130
	v_pk_mul_f32 v[150:151], v[150:151], v[130:131] op_sel:[0,1]
	v_pk_mul_f32 v[152:153], v[152:153], v[130:131] op_sel:[0,1]
	v_pk_fma_f32 v[150:151], v[210:211], v[150:151], v[214:215]
	v_pk_fma_f32 v[152:153], v[212:213], v[152:153], v[216:217]
;   __device__ __forceinline__ void operator()(f32x4 (&acc)[2][2][4][2], int pm, int pn, int wr_, int wc_, int fr_, int fq_, bf16_t* shm, int tid) const {
;     ...
;         for (int ai = 0; ai < 2; ++ai)
; #pragma unroll
;           for (int m = 0; m < 4; ++m) {
;             const int row = pm * 256 + ai * 128 + wr * 64 + m * 16 + fr;
;             const f32x4 v = acc[ai][bj][m][n];
;             f32x4* xp = (f32x4*)(X + (long)row * DM + col);
;             f32x4 xv = *(const f32x4*)(Xr + (long)row * DM + col);
;             if (stats) { const float mu = stats[2 * row], rs = stats[2 * row + 1]; xv = (xv - mu) * rs * lg + lb; }
;             xv = xv * ALPHA + gv * v; *xp = xv;
;             acc[ai][bj][m][n] = xv;
.Lres_r2_skip24:
	v_pk_mul_f32 v[150:151], v[150:151], s[92:93] op_sel_hi:[1,0]
	v_pk_mul_f32 v[152:153], v[152:153], s[92:93] op_sel_hi:[1,0]
	v_pk_fma_f32 v[114:115], v[114:115], v[228:229], v[150:151]
	v_pk_fma_f32 v[116:117], v[116:117], v[230:231], v[152:153]
	s_waitcnt vmcnt(11)
	s_cbranch_vccnz .Lres_r2_skip25
	v_sub_f32_e32 v157, v157, v132
	v_sub_f32_e32 v156, v156, v132
	v_sub_f32_e32 v155, v155, v132
	v_sub_f32_e32 v154, v154, v132
	v_pk_mul_f32 v[154:155], v[154:155], v[132:133] op_sel:[0,1]
	v_pk_mul_f32 v[156:157], v[156:157], v[132:133] op_sel:[0,1]
	v_pk_fma_f32 v[154:155], v[210:211], v[154:155], v[214:215]
	v_pk_fma_f32 v[156:157], v[212:213], v[156:157], v[216:217]
.Lres_r2_skip25:
	v_pk_mul_f32 v[154:155], v[154:155], s[92:93] op_sel_hi:[1,0]
	v_pk_mul_f32 v[156:157], v[156:157], s[92:93] op_sel_hi:[1,0]
	v_pk_fma_f32 v[118:119], v[118:119], v[228:229], v[154:155]
	v_pk_fma_f32 v[120:121], v[120:121], v[230:231], v[156:157]
	s_waitcnt vmcnt(9)
	s_cbranch_vccnz .Lres_r2_skip26
	v_sub_f32_e32 v161, v161, v134
	v_sub_f32_e32 v160, v160, v134
	v_sub_f32_e32 v159, v159, v134
	v_sub_f32_e32 v158, v158, v134
	v_pk_mul_f32 v[158:159], v[158:159], v[134:135] op_sel:[0,1]
	v_pk_mul_f32 v[160:161], v[160:161], v[134:135] op_sel:[0,1]
	v_pk_fma_f32 v[158:159], v[210:211], v[158:159], v[214:215]
	v_pk_fma_f32 v[160:161], v[212:213], v[160:161], v[216:217]
.Lres_r2_skip26:
	v_pk_mul_f32 v[158:159], v[158:159], s[92:93] op_sel_hi:[1,0]
	v_pk_mul_f32 v[160:161], v[160:161], s[92:93] op_sel_hi:[1,0]
	v_pk_fma_f32 v[106:107], v[106:107], v[228:229], v[158:159]
	v_pk_fma_f32 v[108:109], v[108:109], v[230:231], v[160:161]
	s_waitcnt vmcnt(7)
	s_cbranch_vccnz .Lres_r2_skip27
	v_sub_f32_e32 v165, v165, v136
	v_sub_f32_e32 v164, v164, v136
	v_sub_f32_e32 v163, v163, v136
	v_sub_f32_e32 v162, v162, v136
	v_pk_mul_f32 v[162:163], v[162:163], v[136:137] op_sel:[0,1]
	v_pk_mul_f32 v[164:165], v[164:165], v[136:137] op_sel:[0,1]
	v_pk_fma_f32 v[162:163], v[210:211], v[162:163], v[214:215]
	v_pk_fma_f32 v[164:165], v[212:213], v[164:165], v[216:217]
.Lres_r2_skip27:
	v_pk_mul_f32 v[162:163], v[162:163], s[92:93] op_sel_hi:[1,0]
	v_pk_mul_f32 v[164:165], v[164:165], s[92:93] op_sel_hi:[1,0]
	v_pk_fma_f32 v[38:39], v[38:39], v[228:229], v[162:163]
	v_pk_fma_f32 v[40:41], v[40:41], v[230:231], v[164:165]
	s_waitcnt vmcnt(3)
	s_cbranch_vccnz .Lres_r2_skip28
	v_sub_f32_e32 v169, v169, v138
	v_sub_f32_e32 v168, v168, v138
	v_sub_f32_e32 v167, v167, v138
	v_sub_f32_e32 v166, v166, v138
	v_pk_mul_f32 v[166:167], v[166:167], v[138:139] op_sel:[0,1]
	v_pk_mul_f32 v[168:169], v[168:169], v[138:139] op_sel:[0,1]
	v_pk_fma_f32 v[166:167], v[210:211], v[166:167], v[214:215]
	v_pk_fma_f32 v[168:169], v[212:213], v[168:169], v[216:217]
.Lres_r2_skip28:
	v_pk_mul_f32 v[166:167], v[166:167], s[92:93] op_sel_hi:[1,0]
	v_pk_mul_f32 v[168:169], v[168:169], s[92:93] op_sel_hi:[1,0]
	v_pk_fma_f32 v[50:51], v[50:51], v[228:229], v[166:167]
	v_pk_fma_f32 v[52:53], v[52:53], v[230:231], v[168:169]
	s_waitcnt vmcnt(2)
	s_cbranch_vccnz .Lres_r2_skip29
	v_sub_f32_e32 v173, v173, v140
	v_sub_f32_e32 v172, v172, v140
	v_sub_f32_e32 v171, v171, v140
	v_sub_f32_e32 v170, v170, v140
	v_pk_mul_f32 v[170:171], v[170:171], v[140:141] op_sel:[0,1]
	v_pk_mul_f32 v[172:173], v[172:173], v[140:141] op_sel:[0,1]
	v_pk_fma_f32 v[170:171], v[210:211], v[170:171], v[214:215]
	v_pk_fma_f32 v[172:173], v[212:213], v[172:173], v[216:217]
.Lres_r2_skip29:
	v_pk_mul_f32 v[170:171], v[170:171], s[92:93] op_sel_hi:[1,0]
	v_pk_mul_f32 v[172:173], v[172:173], s[92:93] op_sel_hi:[1,0]
	v_pk_fma_f32 v[58:59], v[58:59], v[228:229], v[170:171]
	v_pk_fma_f32 v[60:61], v[60:61], v[230:231], v[172:173]
	s_waitcnt vmcnt(1)
	s_cbranch_vccnz .Lres_r2_skip30
	v_sub_f32_e32 v177, v177, v142
	v_sub_f32_e32 v176, v176, v142
	v_sub_f32_e32 v175, v175, v142
	v_sub_f32_e32 v174, v174, v142
	v_pk_mul_f32 v[174:175], v[174:175], v[142:143] op_sel:[0,1]
	v_pk_mul_f32 v[176:177], v[176:177], v[142:143] op_sel:[0,1]
	v_pk_fma_f32 v[174:175], v[210:211], v[174:175], v[214:215]
	v_pk_fma_f32 v[176:177], v[212:213], v[176:177], v[216:217]
;   __device__ __forceinline__ void operator()(f32x4 (&acc)[2][2][4][2], int pm, int pn, int wr_, int wc_, int fr_, int fq_, bf16_t* shm, int tid) const {
;     ...
;         for (int ai = 0; ai < 2; ++ai)
; #pragma unroll
;           for (int m = 0; m < 4; ++m) {
;             const int row = pm * 256 + ai * 128 + wr * 64 + m * 16 + fr;
;             const f32x4 v = acc[ai][bj][m][n];
;             f32x4* xp = (f32x4*)(X + (long)row * DM + col);
;             f32x4 xv = *(const f32x4*)(Xr + (long)row * DM + col);
;             if (stats) { const float mu = stats[2 * row], rs = stats[2 * row + 1]; xv = (xv - mu) * rs * lg + lb; }
;             xv = xv * ALPHA + gv * v; *xp = xv;
;             acc[ai][bj][m][n] = xv;
;             s1[ai * 4 + m] += (xv[0] + xv[1]) + (xv[2] + xv[3]);
;             s2[ai * 4 + m] += (xv[0] * xv[0] + xv[1] * xv[1]) + (xv[2] * xv[2] + xv[3] * xv[3]);
;           }
;       }
; #pragma unroll
;     for (int i = 0; i < 8; ++i) {
;       s1[i] += __shfl_xor(s1[i], 16); s1[i] += __shfl_xor(s1[i], 32);
;       s2[i] += __shfl_xor(s2[i], 16); s2[i] += __shfl_xor(s2[i], 32);
;       if (fq == 0) red[((i >> 2) * 128 + wr * 64 + (i & 3) * 16 + fr) * 4 + wc] = (f2_t){s1[i], s2[i]};
.Lres_r2_skip30:
	v_pk_mul_f32 v[174:175], v[174:175], s[92:93] op_sel_hi:[1,0]
	v_pk_mul_f32 v[176:177], v[176:177], s[92:93] op_sel_hi:[1,0]
	v_pk_fma_f32 v[70:71], v[70:71], v[228:229], v[174:175]
	v_pk_fma_f32 v[72:73], v[72:73], v[230:231], v[176:177]
	s_waitcnt vmcnt(0)
	s_cbranch_vccnz .Lres_r2_skip31
	v_sub_f32_e32 v181, v181, v144
	v_sub_f32_e32 v180, v180, v144
	v_sub_f32_e32 v179, v179, v144
	v_sub_f32_e32 v178, v178, v144
	v_pk_mul_f32 v[178:179], v[178:179], v[144:145] op_sel:[0,1]
	v_pk_mul_f32 v[180:181], v[180:181], v[144:145] op_sel:[0,1]
	v_pk_fma_f32 v[178:179], v[210:211], v[178:179], v[214:215]
	v_pk_fma_f32 v[180:181], v[212:213], v[180:181], v[216:217]
.Lres_r2_skip31:
	v_pk_mul_f32 v[178:179], v[178:179], s[92:93] op_sel_hi:[1,0]
	v_pk_mul_f32 v[180:181], v[180:181], s[92:93] op_sel_hi:[1,0]
	v_pk_fma_f32 v[122:123], v[122:123], v[228:229], v[178:179]
	v_pk_fma_f32 v[124:125], v[124:125], v[230:231], v[180:181]
.LBB0_547:
	v_mov_b32_e32 v134, v128
	v_mov_b32_e32 v135, v126
	v_mov_b32_e32 v136, v129
	v_mov_b32_e32 v137, v126
	v_pk_add_f32 v[138:139], v[134:135], v[136:137]
	v_pk_mul_f32 v[134:135], v[134:135], v[136:137]
	v_pk_mul_f32 v[136:137], v[126:127], v[126:127]
	v_mov_b32_e32 v139, v135
	v_pk_add_f32 v[134:135], v[126:127], v[126:127] op_sel:[1,0]
	v_mul_f32_e32 v136, v128, v128
	v_mov_b32_e32 v135, v137
	v_pk_fma_f32 v[136:137], v[128:129], v[128:129], v[136:137] op_sel_hi:[1,1,0]
	v_pk_add_f32 v[134:135], v[134:135], v[138:139]
	v_mov_b32_e32 v136, v1
	v_pk_add_f32 v[134:135], v[134:135], v[136:137]
	v_mul_f32_e32 v137, v82, v82
	v_mul_f32_e32 v139, v83, v83
	v_mul_f32_e32 v141, v84, v84
	v_mul_f32_e32 v151, v85, v85
	v_mov_b32_e32 v136, v82
	v_mov_b32_e32 v138, v83
	v_mov_b32_e32 v140, v84
	v_mov_b32_e32 v150, v85
	v_pk_add_f32 v[136:137], v[136:137], v[138:139]
	v_pk_add_f32 v[138:139], v[140:141], v[150:151]
	v_mul_f32_e32 v141, v100, v100
	v_pk_add_f32 v[136:137], v[136:137], v[138:139]
	v_mul_f32_e32 v139, v99, v99
	v_pk_add_f32 v[134:135], v[134:135], v[136:137]
	v_mul_f32_e32 v137, v98, v98
	v_mul_f32_e32 v151, v101, v101
	v_mov_b32_e32 v136, v98
	v_mov_b32_e32 v138, v99
	v_mov_b32_e32 v140, v100
	v_mov_b32_e32 v150, v101
	v_pk_add_f32 v[136:137], v[136:137], v[138:139]
	v_pk_add_f32 v[138:139], v[140:141], v[150:151]
	v_mul_f32_e32 v141, v116, v116
	v_pk_add_f32 v[136:137], v[136:137], v[138:139]
	v_mul_f32_e32 v139, v115, v115
	v_pk_add_f32 v[134:135], v[134:135], v[136:137]
	v_mul_f32_e32 v137, v114, v114
	v_mul_f32_e32 v151, v117, v117
	v_mov_b32_e32 v136, v114
	v_mov_b32_e32 v138, v115
	v_mov_b32_e32 v140, v116
	v_mov_b32_e32 v150, v117
	v_pk_add_f32 v[136:137], v[136:137], v[138:139]
	v_pk_add_f32 v[138:139], v[140:141], v[150:151]
	v_readlane_b32 s0, v253, 26
	v_pk_add_f32 v[136:137], v[136:137], v[138:139]
	v_pk_add_f32 v[136:137], v[134:135], v[136:137]
	v_and_b32_e32 v131, 64, v226
	v_xor_b32_e32 v130, 16, v226
	v_add_u32_e32 v132, 64, v131
	v_cmp_lt_i32_e32 vcc, v130, v132
	v_xor_b32_e32 v133, 32, v226
	v_cndmask_b32_e32 v130, v226, v130, vcc
	v_lshlrev_b32_e32 v134, 2, v130
	v_mov_b32_e32 v130, v136
	v_mov_b32_e32 v131, v137
	s_nop 1
	v_permlane16_swap_b32_e32 v130, v136
	v_permlane16_swap_b32_e32 v131, v137
	v_cmp_lt_i32_e32 vcc, v133, v132
	v_or_b32_e32 v160, v242, v149
	s_waitcnt lgkmcnt(0)
	v_pk_add_f32 v[130:131], v[136:137], v[130:131]
	v_cndmask_b32_e32 v132, v226, v133, vcc
	v_lshlrev_b32_e32 v135, 2, v132
	v_mov_b32_e32 v132, v130
	v_mov_b32_e32 v133, v131
	s_nop 1
	v_permlane32_swap_b32_e32 v132, v130
	v_permlane32_swap_b32_e32 v133, v131
	v_lshl_add_u32 v136, v243, 3, s0
	v_cmp_eq_u32_e32 vcc, 0, v244
	v_lshl_add_u32 v137, v160, 5, v136
	s_and_saveexec_b64 s[0:1], vcc
	s_cbranch_execz .LBB0_549
	s_waitcnt lgkmcnt(0)
	v_pk_add_f32 v[130:131], v[130:131], v[132:133]
	ds_write_b64 v137, v[130:131]

;   __device__ __forceinline__ void operator()(f32x4 (&acc)[2][2][4][2], int pm, int pn, int wr_, int wc_, int fr_, int fq_, bf16_t* shm, int tid) const {
;     ...
;     asm volatile("s_waitcnt vmcnt(0)" ::: "memory");
;     __syncthreads();
;     if (tid == 0) {
;       __hip_atomic_fetch_add(cnt + pm * 16, 1u, __ATOMIC_RELAXED, __HIP_MEMORY_SCOPE_AGENT);
;       unsigned sp = 0;
;       while (__hip_atomic_load(cnt + pm * 16, __ATOMIC_RELAXED, __HIP_MEMORY_SCOPE_AGENT) < 4u * gen) { __builtin_amdgcn_s_sleep(1); if (++sp > (1u << 22)) break; }
;     }
.LBB0_565:
	s_or_b64 exec, exec, s[0:1]
	s_waitcnt vmcnt(0)
	v_cmp_eq_u32_e32 vcc, 0, v148
	s_barrier
	v_readlane_b32 s98, v250, 0
	s_cmp_eq_u32 s98, 0
	s_cbranch_scc1 .Lres_r2_dq
	global_store_dwordx4 v218, v[98:101], s[54:55] offset:512
	global_store_dwordx4 v219, v[102:105], s[54:55] offset:512
	global_store_dwordx4 v224, v[90:93], s[54:55] offset:512
	global_store_dwordx4 v225, v[22:25], s[54:55] offset:512
	global_store_dwordx4 v227, v[34:37], s[54:55] offset:512
	global_store_dwordx4 v232, v[42:45], s[54:55] offset:512
	global_store_dwordx4 v233, v[62:65], s[54:55] offset:512
	global_store_dwordx4 v245, v[74:77], s[54:55] offset:512
	global_store_dwordx4 v218, v[114:117], s[54:55] offset:576
	global_store_dwordx4 v219, v[118:121], s[54:55] offset:576
	global_store_dwordx4 v224, v[106:109], s[54:55] offset:576
	global_store_dwordx4 v225, v[38:41], s[54:55] offset:576
	global_store_dwordx4 v227, v[50:53], s[54:55] offset:576
	global_store_dwordx4 v232, v[58:61], s[54:55] offset:576
	global_store_dwordx4 v233, v[70:73], s[54:55] offset:576
	global_store_dwordx4 v245, v[122:125], s[54:55] offset:576
.Lres_r2_dq:
	s_and_saveexec_b64 s[0:1], vcc
	s_cbranch_execz .LBB0_576
	s_lshl_b32 s12, s4, 4
	s_mov_b64 s[14:15], exec
	s_ashr_i32 s13, s12, 31
	s_lshl_b64 s[12:13], s[12:13], 2
	v_readlane_b32 s26, v253, 36
	v_mbcnt_lo_u32_b32 v130, s14, 0
	v_readlane_b32 s27, v253, 37
	s_add_u32 s12, s26, s12
	v_mbcnt_hi_u32_b32 v130, s15, v130
	s_addc_u32 s13, s27, s13
	v_cmp_eq_u32_e32 vcc, 0, v130
	s_and_saveexec_b64 s[40:41], vcc
	s_cbranch_execz .LBB0_568
	s_bcnt1_i32_b64 s5, s[14:15]
	v_mov_b32_e32 v130, s5
	global_atomic_add v1, v130, s[12:13]

; __device__ __forceinline__ unsigned pk2(float lo, float hi) { const f2_t v = {lo, hi}; return __builtin_bit_cast(unsigned, __builtin_convertvector(v, bf2_t)); }
;   __device__ __forceinline__ void operator()(f32x4 (&acc)[2][2][4][2], int pm, int pn, int wr_, int wc_, int fr_, int fq_, bf16_t* shm, int tid) const {
;     ...
;     if (tid < 256) {
;       float S1 = 0.f, S2 = 0.f;
; #pragma unroll
;       for (int q = 0; q < 4; ++q) { const f2_t t = __builtin_bit_cast(f2_t, __hip_atomic_load(xch + ((long)pm * 4 + q) * 256 + tid, __ATOMIC_RELAXED, __HIP_MEMORY_SCOPE_AGENT)); S1 += t[0]; S2 += t[1]; }
;       const float mu = S1 * (1.f / 1024.f), var = fmaxf(S2 * (1.f / 1024.f) - mu * mu, 0.f), rs = rsqrtf(var + EPS);
;       rst[tid] = (f2_t){mu, rs};
;       if (pn == 0 && !outp) { lnst[2 * (pm * 256 + tid)] = mu; lnst[2 * (pm * 256 + tid) + 1] = rs; }
;     }
;     __syncthreads();
; #pragma unroll
;     for (int bj = 0; bj < 2; ++bj)
; #pragma unroll
;       for (int n = 0; n < 2; ++n) {
;         asm volatile("" ::: "memory");
;         const int col = pn * 256 + bj * 128 + wc * 32 + n * 16 + fq * 4;
;         const f32x4 gg = *(const f32x4*)(ng + col), bb = *(const f32x4*)(nb + col);
;         f32x4 sh = {0.f, 0.f, 0.f, 0.f}, sc = {0.f, 0.f, 0.f, 0.f};
;         if (!outp) { sh = *(const f32x4*)(msh + bio + col); sc = *(const f32x4*)(msc + bio + col); }
; #pragma unroll
;         for (int ai = 0; ai < 2; ++ai)
; #pragma unroll
;           for (int m = 0; m < 4; ++m) {
;             const int rl = ai * 128 + wr * 64 + m * 16 + fr, row = pm * 256 + rl;
;             const f2_t st = rst[rl];
;             f32x4 y = (acc[ai][bj][m][n] - st[0]) * st[1] * gg + bb;
;             if (outp) { *(f32x4*)(outp + (long)row * DM + col) = y; }
;             else {
;               y = y * (sc + 1.f) + sh;
;               u32x2 w; w.x = pk2(y[0], y[1]); w.y = pk2(y[2], y[3]);
;               *(u32x2*)(H + (long)row * DM + col) = w;
;               if (HA && (rl == 0 || rl == 255)) *(u32x2*)(HA + (long)(pm * 2 + (rl == 255)) * DM + col) = w;
.LBB0_579:
	s_or_b64 exec, exec, s[0:1]
	v_readlane_b32 s98, v250, 0
	s_cmp_lg_u32 s98, 0
	s_cbranch_scc1 .Lres_r2_dq0
	v_readlane_b32 s98, v252, 24
	v_readlane_b32 s99, v252, 25
	s_nop 4
	global_store_dwordx4 v218, v[98:101], s[98:99] offset:512
	global_store_dwordx4 v219, v[102:105], s[98:99] offset:512
	global_store_dwordx4 v224, v[90:93], s[98:99] offset:512
	global_store_dwordx4 v225, v[22:25], s[98:99] offset:512
	global_store_dwordx4 v227, v[34:37], s[98:99] offset:512
	global_store_dwordx4 v232, v[42:45], s[98:99] offset:512
	global_store_dwordx4 v233, v[62:65], s[98:99] offset:512
	global_store_dwordx4 v245, v[74:77], s[98:99] offset:512
	global_store_dwordx4 v218, v[114:117], s[98:99] offset:576
	global_store_dwordx4 v219, v[118:121], s[98:99] offset:576
	global_store_dwordx4 v224, v[106:109], s[98:99] offset:576
	global_store_dwordx4 v225, v[38:41], s[98:99] offset:576
	global_store_dwordx4 v227, v[50:53], s[98:99] offset:576
	global_store_dwordx4 v232, v[58:61], s[98:99] offset:576
	global_store_dwordx4 v233, v[70:73], s[98:99] offset:576
	global_store_dwordx4 v245, v[122:125], s[98:99] offset:576
.Lres_r2_dq0:
	s_add_u32 s0, s29, s6
	s_addc_u32 s1, s30, s7
	s_add_u32 s6, s24, s6
	s_addc_u32 s7, s28, s7
	s_waitcnt lgkmcnt(0)
	s_barrier
	v_lshl_add_u64 v[144:145], s[78:79], 0, v[146:147]
	v_lshl_add_u64 v[148:149], s[42:43], 0, v[146:147]
	v_lshl_add_u64 v[150:151], s[0:1], 0, v[146:147]
	v_lshl_add_u64 v[146:147], s[6:7], 0, v[146:147]
	global_load_dwordx4 v[130:133], v[144:145], off
	global_load_dwordx4 v[134:137], v[148:149], off
	global_load_dwordx4 v[138:141], v[146:147], off
	global_load_dwordx4 v[154:157], v[150:151], off
	global_load_dwordx4 v[176:179], v[150:151], off offset:64
	global_load_dwordx4 v[180:183], v[144:145], off offset:64
	global_load_dwordx4 v[184:187], v[148:149], off offset:64
	global_load_dwordx4 v[188:191], v[146:147], off offset:64
	global_load_dwordx4 v[192:195], v[150:151], off offset:512
	global_load_dwordx4 v[196:199], v[144:145], off offset:512
	global_load_dwordx4 v[200:203], v[148:149], off offset:512
	global_load_dwordx4 v[204:207], v[146:147], off offset:512
	global_load_dwordx4 v[208:211], v[150:151], off offset:576
	global_load_dwordx4 v[212:215], v[144:145], off offset:576
	global_load_dwordx4 v[216:219], v[148:149], off offset:576
	global_load_dwordx4 v[228:231], v[146:147], off offset:576
	v_readlane_b32 s44, v252, 20
	v_lshlrev_b32_e32 v0, 1, v0
	v_readlane_b32 s50, v252, 26
	v_readlane_b32 s51, v252, 27
	v_readlane_b32 s54, v252, 30
	v_readlane_b32 s55, v252, 31
	v_add_u32_e32 v158, s82, v160
	v_ashrrev_i32_e32 v159, 31, v158
	v_lshl_add_u64 v[142:143], s[54:55], 0, v[0:1]
	v_readlane_b32 s0, v251, 7
	v_cmp_eq_u32_e32 vcc, 0, v160
	v_readlane_b32 s1, v251, 8
	s_lshl_b32 s4, s4, 1
	s_and_b64 s[6:7], s[0:1], vcc
	v_readlane_b32 s45, v252, 21
	v_readlane_b32 s46, v252, 22
	v_readlane_b32 s47, v252, 23
	v_readlane_b32 s48, v252, 24
	v_readlane_b32 s49, v252, 25
	v_readlane_b32 s52, v252, 28
	v_readlane_b32 s53, v252, 29
	v_readlane_b32 s56, v252, 32
	v_readlane_b32 s57, v252, 33
	v_readlane_b32 s58, v252, 34
	v_readlane_b32 s59, v252, 35
	s_waitcnt vmcnt(0)
	v_pk_add_f32 v[152:153], v[156:157], 1.0 op_sel_hi:[1,0]
	v_lshl_add_u64 v[156:157], s[50:51], 0, v[0:1]
	v_lshl_add_u32 v0, v160, 3, 16
	v_add_u32_e32 v0, 0x22000, v0
	ds_read_b64 v[162:163], v0
	v_pk_add_f32 v[154:155], v[154:155], 1.0 op_sel_hi:[1,0]
	s_waitcnt lgkmcnt(0)
	v_sub_f32_e32 v127, v127, v162
	v_sub_f32_e32 v126, v126, v162
	v_sub_f32_e32 v129, v129, v162
	v_sub_f32_e32 v128, v128, v162
	v_pk_mul_f32 v[126:127], v[162:163], v[126:127] op_sel:[1,0]
	v_pk_mul_f32 v[128:129], v[162:163], v[128:129] op_sel:[1,0]
	v_pk_fma_f32 v[126:127], v[130:131], v[126:127], v[134:135]
	v_pk_fma_f32 v[128:129], v[132:133], v[128:129], v[136:137]
	v_pk_fma_f32 v[126:127], v[154:155], v[126:127], v[138:139]
	v_pk_fma_f32 v[162:163], v[152:153], v[128:129], v[140:141]
	v_cvt_pk_bf16_f32 v128, v126, v127
	v_lshlrev_b64 v[126:127], 11, v[158:159]
	v_cvt_pk_bf16_f32 v129, v162, v163
	v_lshl_add_u64 v[126:127], v[156:157], 0, v[126:127]
	global_store_dwordx2 v[126:127], v[128:129], off
	s_and_saveexec_b64 s[0:1], s[6:7]
	s_cbranch_execz .LBB0_581
	s_ashr_i32 s5, s4, 31
	s_lshl_b64 s[8:9], s[4:5], 11
	v_lshl_add_u64 v[162:163], v[142:143], 0, s[8:9]
	global_store_dwordx2 v[162:163], v[128:129], off
